# PH0 attention: next item Q rows prefetched right after last PV MFMA into regs dead until score part, v_mov to operand regs before first score MFMA; loop top waits only for K loads
# baseline (speedup 1.0000x reference)
.LBB0_713:
	v_add_u32_e32 v22, s93, v107
	v_add_u32_e32 v23, 0xa000, v47
	v_add_u32_e32 v30, 0xc000, v47
	v_add_u32_e32 v31, 0xe000, v47
	v_add_u32_e32 v38, 0x10000, v47
	v_add_u32_e32 v39, 0x12000, v47
	v_add_u32_e32 v48, 0x14000, v47
	v_add_u32_e32 v47, 0x16000, v47
	v_lshl_add_u32 v22, v22, s83, v46
	v_lshl_add_u32 v26, v23, s83, v46
	v_lshl_add_u32 v30, v30, s83, v46
	v_lshl_add_u32 v34, v31, s83, v46
	v_lshl_add_u32 v38, v38, s83, v46
	v_lshl_add_u32 v42, v39, s83, v46
	v_lshl_add_u32 v48, v48, s83, v46
	s_waitcnt vmcnt(16)
	v_lshl_add_u32 v50, v47, s83, v46
	global_load_dwordx4 v[22:25], v22, s[70:71]
	s_nop 0
	global_load_dwordx4 v[26:29], v26, s[70:71]
	s_nop 0
	global_load_dwordx4 v[30:33], v30, s[70:71]
	s_nop 0
	global_load_dwordx4 v[34:37], v34, s[70:71]
	s_nop 0
	global_load_dwordx4 v[38:41], v38, s[70:71]
	s_nop 0
	global_load_dwordx4 v[42:45], v42, s[70:71]
	s_nop 0
	global_load_dwordx4 v[46:49], v48, s[70:71]
	s_nop 0
	global_load_dwordx4 v[50:53], v50, s[70:71]
	v_and_b32_e32 v55, 15, v54
	v_lshrrev_b32_e32 v2, 4, v54
	s_ashr_i32 s0, s8, 8
	s_bfe_u32 s1, s8, 0x20006
	v_bfe_u32 v56, v54, 4, 2
	s_lshl_b32 s8, s0, 3
	s_lshl_b32 s9, s1, 1
	v_bitop3_b32 v2, v2, v55, 3 bitop3:0x6c
	s_or_b32 s10, s9, s8
	v_lshlrev_b32_e32 v58, 4, v2
	v_bitop3_b32 v2, v56, v55, 4 bitop3:0x36
	s_lshl_b32 s8, s10, 12
	v_lshlrev_b32_e32 v59, 4, v2
	v_bitop3_b32 v2, v56, v55, 8 bitop3:0x36
	v_lshlrev_b32_e32 v62, 3, v54
	s_add_i32 s8, s8, 0
	v_lshlrev_b32_e32 v60, 4, v2
	v_bitop3_b32 v2, v56, v55, 12 bitop3:0x36
	v_and_b32_e32 v63, 16, v62
	v_lshlrev_b32_e32 v4, 2, v56
	v_lshl_add_u32 v57, v55, 8, s8
	v_lshlrev_b32_e32 v61, 4, v2
	v_bfe_u32 v2, v54, 2, 2
	s_lshl_b32 s8, s10, 4
	v_add_u32_e32 v63, 0, v63
	v_and_or_b32 v5, v4, 4, v2
	v_or3_b32 v2, s8, v4, v2
	v_and_or_b32 v62, v62, 8, v63
	v_lshl_add_u32 v2, v2, 8, v62
	v_lshlrev_b32_e32 v5, 5, v5
	s_movk_i32 s8, 0x60
	v_xad_u32 v112, v5, s8, v2
	s_movk_i32 s8, 0x80
	v_xad_u32 v113, v5, s8, v2
	s_movk_i32 s8, 0xa0
	v_xad_u32 v114, v5, s8, v2
	s_movk_i32 s8, 0xc0
	s_lshl_b32 s20, s0, 7
	s_lshl_b32 s1, s1, 5
	v_xad_u32 v115, v5, s8, v2
	s_movk_i32 s8, 0xe0
	s_cmp_gt_i32 s10, 7
	v_xad_u32 v116, v5, s8, v2
	s_cselect_b64 s[8:9], -1, 0
	s_cmp_gt_i32 s10, 6
	s_cselect_b64 s[12:13], -1, 0
	s_cmp_gt_i32 s10, 5
	s_cselect_b64 s[14:15], -1, 0
	s_cmp_gt_i32 s10, 4
	s_cselect_b64 s[26:27], -1, 0
	s_cmp_gt_i32 s10, 3
	s_cselect_b64 s[34:35], -1, 0
	s_cmp_gt_i32 s10, 2
	s_cselect_b64 s[36:37], -1, 0
	s_cmp_gt_i32 s10, 1
	s_cselect_b64 s[56:57], -1, 0
	s_cmp_gt_i32 s10, 0
	v_add_u32_e32 v109, v2, v5
	v_xad_u32 v110, v5, 32, v2
	v_xad_u32 v111, v5, 64, v2
	v_ashrrev_i32_e32 v2, 4, v54
	s_cselect_b64 s[62:63], -1, 0
	s_cmp_gt_i32 s0, -1
	v_xor_b32_e32 v5, v2, v54
	s_cselect_b64 s[66:67], -1, 0
	s_cmp_gt_i32 s10, -2
	v_sub_u32_e32 v62, v4, v55
	v_lshl_add_u32 v4, v2, 8, 0
	v_lshlrev_b32_e32 v5, 4, v5
	v_lshlrev_b32_e32 v2, 1, v2
	s_cselect_b64 s[10:11], -1, 0
	s_or_b32 s0, s20, s1
	v_and_b32_e32 v5, 0xf0, v5
	v_bitop3_b32 v2, v2, v55, 14 bitop3:0x6c
	v_or_b32_e32 v127, s0, v55
	v_readlane_b32 s0, v241, 47
	v_add_u32_e32 v117, v4, v5
	v_lshl_add_u32 v118, v2, 4, v4
	v_lshlrev_b32_e32 v2, 3, v56
	v_lshlrev_b32_e32 v4, 4, v56
	v_mov_b32_e32 v5, v3
	v_mov_b32_e32 v132, s0
	v_readlane_b32 s0, v241, 46
	v_lshl_add_u64 v[94:95], s[72:73], 0, v[4:5]
	v_lshl_add_u64 v[96:97], s[72:73], 0, v[2:3]
	v_cmp_eq_u32_e64 s[38:39], 0, v56
	v_add_u32_e32 v119, 0x10000, v117
	v_add_u32_e32 v120, 0x12000, v117
	v_add_u32_e32 v121, 0x14000, v117
	v_add_u32_e32 v122, 0x16000, v117
	v_cmp_lt_i32_e64 s[40:41], -1, v62
	v_cmp_lt_i32_e64 s[42:43], -2, v62
	v_cmp_lt_i32_e64 s[44:45], -3, v62
	v_cmp_lt_i32_e64 s[46:47], -4, v62
	v_cmp_gt_i32_e64 s[48:49], 1, v62
	v_cmp_gt_i32_e64 s[50:51], 0, v62
	v_cmp_gt_i32_e64 s[52:53], -1, v62
	v_cmp_gt_i32_e64 s[54:55], -2, v62
	v_add_u32_e32 v123, 0x10000, v118
	v_add_u32_e32 v124, 0x12000, v118
	v_add_u32_e32 v125, 0x14000, v118
	v_add_u32_e32 v126, 0x16000, v118
	v_add_u32_e32 v128, v57, v58
	v_add_u32_e32 v129, v57, v59
	v_add_u32_e32 v130, v57, v60
	v_add_u32_e32 v131, v57, v61
	v_readlane_b32 s79, v241, 49
	s_mov_b32 s30, s0
	v_readlane_b32 s20, v241, 45
	v_readlane_b32 s31, v241, 44
	v_readlane_b32 s78, v242, 10
	s_lshl_b32 s0, s31, 1
	v_lshl_add_u32 v2, s79, 8, v127
	s_lshl_b32 s24, s20, 4
	s_lshl_b32 s1, s31, 6
	s_add_i32 s24, s24, s30
	v_lshlrev_b32_e32 v54, s0, v2
	v_or_b32_e32 v2, 16, v2
	s_add_i32 s24, s24, s1
	v_lshlrev_b32_e32 v2, s0, v2
	s_ashr_i32 s25, s24, 31
	v_add_u32_e32 v102, v54, v132
	v_add_u32_e32 v98, v2, v132
	s_lshl_b64 s[24:25], s[24:25], 20
	v_ashrrev_i32_e32 v103, 31, v102
	v_ashrrev_i32_e32 v99, 31, v98
	v_lshl_add_u64 v[4:5], v[94:95], 0, s[24:25]
	v_lshlrev_b64 v[104:105], 8, v[102:103]
	v_lshlrev_b64 v[100:101], 8, v[98:99]
	v_lshl_add_u64 v[66:67], v[4:5], 0, v[104:105]
	v_lshl_add_u64 v[4:5], v[4:5], 0, v[100:101]
	global_load_dwordx4 v[204:207], v[66:67], off
	global_load_dwordx4 v[208:211], v[66:67], off offset:64
	global_load_dwordx4 v[212:215], v[66:67], off offset:128
	s_nop 0
	global_load_dwordx4 v[216:219], v[66:67], off offset:192
	s_nop 0
	global_load_dwordx4 v[220:223], v[4:5], off
	global_load_dwordx4 v[224:227], v[4:5], off offset:64
	global_load_dwordx4 v[228:231], v[4:5], off offset:128
	global_load_dwordx4 v[192:195], v[4:5], off offset:192
	s_lshl_b32 s1, s20, 24
	s_lshl_b32 s60, s30, 20
	s_waitcnt vmcnt(16)
	ds_write_b128 v117, v[6:9]
	ds_write_b128 v117, v[10:13] offset:8192
	ds_write_b128 v117, v[14:17] offset:16384
	ds_write_b128 v117, v[18:21] offset:24576
	s_waitcnt vmcnt(15)
	ds_write_b128 v117, v[22:25] offset:32768
	s_waitcnt vmcnt(14)
	ds_write_b128 v117, v[26:29] offset:40960
	s_waitcnt vmcnt(13)
	ds_write_b128 v117, v[30:33] offset:49152
	s_waitcnt vmcnt(12)
	ds_write_b128 v117, v[34:37] offset:57344
	s_waitcnt vmcnt(11)
	ds_write_b128 v119, v[38:41]
	s_waitcnt vmcnt(10)
	ds_write_b128 v120, v[42:45]
	s_waitcnt vmcnt(9)
	ds_write_b128 v121, v[46:49]
	s_waitcnt vmcnt(8)
	ds_write_b128 v122, v[50:53]
	s_mov_b32 s98, 0x7f000000
	s_branch .Lph0_join

.LBB0_715:
	s_lshl_b32 s0, s31, 1
	v_lshl_add_u32 v2, s79, 8, v127
	s_lshl_b32 s24, s20, 4
	s_lshl_b32 s1, s31, 6
	s_add_i32 s24, s24, s30
	v_lshlrev_b32_e32 v54, s0, v2
	v_or_b32_e32 v2, 16, v2
	s_add_i32 s24, s24, s1
	v_lshlrev_b32_e32 v2, s0, v2
	s_ashr_i32 s25, s24, 31
	v_add_u32_e32 v102, v54, v132
	v_add_u32_e32 v98, v2, v132
	s_lshl_b64 s[24:25], s[24:25], 20
	v_ashrrev_i32_e32 v103, 31, v102
	v_ashrrev_i32_e32 v99, 31, v98
	v_lshl_add_u64 v[4:5], v[94:95], 0, s[24:25]
	v_lshlrev_b64 v[104:105], 8, v[102:103]
	v_lshlrev_b64 v[100:101], 8, v[98:99]
	v_lshl_add_u64 v[4:5], v[4:5], 0, v[100:101]
	s_lshl_b32 s1, s20, 24
	s_lshl_b32 s60, s30, 20
	s_waitcnt vmcnt(24)
	ds_write_b128 v117, v[6:9]
	ds_write_b128 v117, v[10:13] offset:8192
	ds_write_b128 v117, v[14:17] offset:16384
	ds_write_b128 v117, v[18:21] offset:24576
	ds_write_b128 v117, v[22:25] offset:32768
	ds_write_b128 v117, v[26:29] offset:40960
	ds_write_b128 v117, v[30:33] offset:49152
	ds_write_b128 v117, v[34:37] offset:57344
	ds_write_b128 v119, v[38:41]
	ds_write_b128 v120, v[42:45]
	ds_write_b128 v121, v[46:49]
	ds_write_b128 v122, v[50:53]
	s_mov_b32 s98, 0x7f000001

.LBB0_720:
	ds_read_b128 v[86:89], v128
	ds_read_b128 v[90:93], v128 offset:4096
	ds_read_b128 v[134:137], v129
	ds_read_b128 v[138:141], v129 offset:4096
	ds_read_b128 v[142:145], v130
	ds_read_b128 v[146:149], v130 offset:4096
	ds_read_b128 v[150:153], v131
	ds_read_b128 v[154:157], v131 offset:4096
	s_cmp_eq_u32 s98, 0x7f000000
	s_cbranch_scc1 .Lph0_qfirst
	s_waitcnt vmcnt(24)
	s_branch .Lph0_qmov
.Lph0_qfirst:
	s_waitcnt vmcnt(8)
.Lph0_qmov:
	v_mov_b64_e32 v[54:55], v[204:205]
	v_mov_b64_e32 v[56:57], v[206:207]
	v_mov_b64_e32 v[58:59], v[208:209]
	v_mov_b64_e32 v[60:61], v[210:211]
	v_mov_b64_e32 v[62:63], v[212:213]
	v_mov_b64_e32 v[64:65], v[214:215]
	v_mov_b64_e32 v[66:67], v[216:217]
	v_mov_b64_e32 v[68:69], v[218:219]
	v_mov_b64_e32 v[70:71], v[220:221]
	v_mov_b64_e32 v[72:73], v[222:223]
	v_mov_b64_e32 v[74:75], v[224:225]
	v_mov_b64_e32 v[76:77], v[226:227]
	v_mov_b64_e32 v[78:79], v[228:229]
	v_mov_b64_e32 v[80:81], v[230:231]
	v_mov_b64_e32 v[82:83], v[192:193]
	v_mov_b64_e32 v[84:85], v[194:195]
	s_nop 1
	s_waitcnt lgkmcnt(7)
	v_mfma_f32_16x16x32_bf16 v[86:89], v[86:89], v[54:57], 0
	s_waitcnt lgkmcnt(5)
	v_mfma_f32_16x16x32_bf16 v[86:89], v[134:137], v[58:61], v[86:89]
	s_waitcnt lgkmcnt(3)
	v_mfma_f32_16x16x32_bf16 v[86:89], v[142:145], v[62:65], v[86:89]
	s_waitcnt lgkmcnt(1)
	v_mfma_f32_16x16x32_bf16 v[86:89], v[150:153], v[66:69], v[86:89]
	ds_read_b128 v[134:137], v128 offset:8192
	ds_read_b128 v[142:145], v129 offset:8192
	ds_read_b128 v[150:153], v130 offset:8192
	ds_read_b128 v[158:161], v131 offset:8192
	v_mfma_f32_16x16x32_bf16 v[168:171], v[90:93], v[54:57], 0
	s_nop 0
	v_mfma_f32_16x16x32_bf16 v[90:93], v[90:93], v[70:73], 0
	s_nop 0
	v_mfma_f32_16x16x32_bf16 v[90:93], v[138:141], v[74:77], v[90:93]
	v_mfma_f32_16x16x32_bf16 v[168:171], v[138:141], v[58:61], v[168:171]
	s_nop 0
	v_mfma_f32_16x16x32_bf16 v[90:93], v[146:149], v[78:81], v[90:93]
	v_mfma_f32_16x16x32_bf16 v[168:171], v[146:149], v[62:65], v[168:171]
	s_waitcnt lgkmcnt(4)
	v_mfma_f32_16x16x32_bf16 v[90:93], v[154:157], v[82:85], v[90:93]
	v_mfma_f32_16x16x32_bf16 v[168:171], v[154:157], v[66:69], v[168:171]
	ds_read_b128 v[138:141], v128 offset:12288
	ds_read_b128 v[146:149], v129 offset:12288
	ds_read_b128 v[154:157], v130 offset:12288
	ds_read_b128 v[172:175], v131 offset:12288
	s_waitcnt lgkmcnt(7)
	v_mfma_f32_16x16x32_bf16 v[176:179], v[134:137], v[54:57], 0
	v_mfma_f32_16x16x32_bf16 v[134:137], v[134:137], v[70:73], 0
	s_waitcnt lgkmcnt(6)
	v_mfma_f32_16x16x32_bf16 v[134:137], v[142:145], v[74:77], v[134:137]
	v_mfma_f32_16x16x32_bf16 v[176:179], v[142:145], v[58:61], v[176:179]
	s_waitcnt lgkmcnt(5)
	v_mfma_f32_16x16x32_bf16 v[134:137], v[150:153], v[78:81], v[134:137]
	v_mfma_f32_16x16x32_bf16 v[176:179], v[150:153], v[62:65], v[176:179]
	s_waitcnt lgkmcnt(4)
	v_mfma_f32_16x16x32_bf16 v[134:137], v[158:161], v[82:85], v[134:137]
	v_mfma_f32_16x16x32_bf16 v[176:179], v[158:161], v[66:69], v[176:179]
	ds_read_b128 v[142:145], v128 offset:16384
	ds_read_b128 v[150:153], v129 offset:16384
	ds_read_b128 v[158:161], v130 offset:16384
	ds_read_b128 v[180:183], v131 offset:16384
	s_waitcnt lgkmcnt(7)
	v_mfma_f32_16x16x32_bf16 v[184:187], v[138:141], v[54:57], 0
	v_mfma_f32_16x16x32_bf16 v[138:141], v[138:141], v[70:73], 0
	s_waitcnt lgkmcnt(6)
	v_mfma_f32_16x16x32_bf16 v[184:187], v[146:149], v[58:61], v[184:187]
	v_mfma_f32_16x16x32_bf16 v[138:141], v[146:149], v[74:77], v[138:141]
	s_waitcnt lgkmcnt(5)
	v_mfma_f32_16x16x32_bf16 v[184:187], v[154:157], v[62:65], v[184:187]
	v_mfma_f32_16x16x32_bf16 v[138:141], v[154:157], v[78:81], v[138:141]
	s_waitcnt lgkmcnt(4)
	v_mfma_f32_16x16x32_bf16 v[184:187], v[172:175], v[66:69], v[184:187]
	v_mfma_f32_16x16x32_bf16 v[138:141], v[172:175], v[82:85], v[138:141]
	ds_read_b128 v[146:149], v128 offset:20480
	ds_read_b128 v[154:157], v129 offset:20480
	ds_read_b128 v[172:175], v130 offset:20480
	ds_read_b128 v[188:191], v131 offset:20480
	s_waitcnt lgkmcnt(7)
	v_mfma_f32_16x16x32_bf16 v[192:195], v[142:145], v[54:57], 0
	v_mfma_f32_16x16x32_bf16 v[142:145], v[142:145], v[70:73], 0
	s_waitcnt lgkmcnt(6)
	v_mfma_f32_16x16x32_bf16 v[192:195], v[150:153], v[58:61], v[192:195]
	v_mfma_f32_16x16x32_bf16 v[142:145], v[150:153], v[74:77], v[142:145]
	s_waitcnt lgkmcnt(5)
	v_mfma_f32_16x16x32_bf16 v[192:195], v[158:161], v[62:65], v[192:195]
	v_mfma_f32_16x16x32_bf16 v[142:145], v[158:161], v[78:81], v[142:145]
	s_waitcnt lgkmcnt(4)
	v_mfma_f32_16x16x32_bf16 v[192:195], v[180:183], v[66:69], v[192:195]
	v_mfma_f32_16x16x32_bf16 v[142:145], v[180:183], v[82:85], v[142:145]
	ds_read_b128 v[150:153], v128 offset:24576
	ds_read_b128 v[158:161], v129 offset:24576
	ds_read_b128 v[180:183], v130 offset:24576
	ds_read_b128 v[204:207], v131 offset:24576
	s_waitcnt lgkmcnt(7)
	v_mfma_f32_16x16x32_bf16 v[208:211], v[146:149], v[54:57], 0
	v_mfma_f32_16x16x32_bf16 v[146:149], v[146:149], v[70:73], 0
	s_waitcnt lgkmcnt(6)
	v_mfma_f32_16x16x32_bf16 v[208:211], v[154:157], v[58:61], v[208:211]
	v_mfma_f32_16x16x32_bf16 v[146:149], v[154:157], v[74:77], v[146:149]
	s_waitcnt lgkmcnt(5)
	v_mfma_f32_16x16x32_bf16 v[208:211], v[172:175], v[62:65], v[208:211]
	v_mfma_f32_16x16x32_bf16 v[146:149], v[172:175], v[78:81], v[146:149]
	s_waitcnt lgkmcnt(4)
	v_mfma_f32_16x16x32_bf16 v[208:211], v[188:191], v[66:69], v[208:211]
	v_mfma_f32_16x16x32_bf16 v[146:149], v[188:191], v[82:85], v[146:149]
	ds_read_b128 v[154:157], v128 offset:28672
	ds_read_b128 v[172:175], v129 offset:28672
	ds_read_b128 v[188:191], v130 offset:28672
	ds_read_b128 v[212:215], v131 offset:28672
	s_waitcnt lgkmcnt(7)
	v_mfma_f32_16x16x32_bf16 v[216:219], v[150:153], v[54:57], 0
	v_mfma_f32_16x16x32_bf16 v[150:153], v[150:153], v[70:73], 0
	s_waitcnt lgkmcnt(6)
	v_mfma_f32_16x16x32_bf16 v[216:219], v[158:161], v[58:61], v[216:219]
	v_mfma_f32_16x16x32_bf16 v[150:153], v[158:161], v[74:77], v[150:153]
	s_waitcnt lgkmcnt(5)
	v_mfma_f32_16x16x32_bf16 v[216:219], v[180:183], v[62:65], v[216:219]
	v_mfma_f32_16x16x32_bf16 v[150:153], v[180:183], v[78:81], v[150:153]
	s_waitcnt lgkmcnt(4)
	v_mfma_f32_16x16x32_bf16 v[216:219], v[204:207], v[66:69], v[216:219]
	v_mfma_f32_16x16x32_bf16 v[150:153], v[204:207], v[82:85], v[150:153]
	ds_read_b128 v[158:161], v128 offset:32768
	ds_read_b128 v[180:183], v129 offset:32768
	ds_read_b128 v[204:207], v130 offset:32768
	ds_read_b128 v[220:223], v131 offset:32768
	s_waitcnt lgkmcnt(7)
	v_mfma_f32_16x16x32_bf16 v[224:227], v[154:157], v[54:57], 0
	v_mfma_f32_16x16x32_bf16 v[154:157], v[154:157], v[70:73], 0
	s_waitcnt lgkmcnt(6)
	v_mfma_f32_16x16x32_bf16 v[224:227], v[172:175], v[58:61], v[224:227]
	v_mfma_f32_16x16x32_bf16 v[154:157], v[172:175], v[74:77], v[154:157]
	s_waitcnt lgkmcnt(5)
	v_mfma_f32_16x16x32_bf16 v[224:227], v[188:191], v[62:65], v[224:227]
	v_mfma_f32_16x16x32_bf16 v[154:157], v[188:191], v[78:81], v[154:157]
	s_waitcnt lgkmcnt(4)
	v_mfma_f32_16x16x32_bf16 v[224:227], v[212:215], v[66:69], v[224:227]
	v_mfma_f32_16x16x32_bf16 v[154:157], v[212:215], v[82:85], v[154:157]
	ds_read_b128 v[172:175], v128 offset:36864
	ds_read_b128 v[188:191], v129 offset:36864
	ds_read_b128 v[212:215], v130 offset:36864
	ds_read_b128 v[228:231], v131 offset:36864
	s_waitcnt lgkmcnt(7)
	v_mfma_f32_16x16x32_bf16 v[54:57], v[158:161], v[54:57], 0
	s_waitcnt lgkmcnt(6)
	v_mfma_f32_16x16x32_bf16 v[54:57], v[180:183], v[58:61], v[54:57]
	v_mfma_f32_16x16x32_bf16 v[58:61], v[158:161], v[70:73], 0
	v_mfma_f32_16x16x32_bf16 v[58:61], v[180:183], v[74:77], v[58:61]
	s_waitcnt lgkmcnt(5)
	v_mfma_f32_16x16x32_bf16 v[54:57], v[204:207], v[62:65], v[54:57]
	v_mfma_f32_16x16x32_bf16 v[58:61], v[204:207], v[78:81], v[58:61]
	s_waitcnt lgkmcnt(4)
	v_mfma_f32_16x16x32_bf16 v[54:57], v[220:223], v[66:69], v[54:57]
	v_mfma_f32_16x16x32_bf16 v[58:61], v[220:223], v[82:85], v[58:61]
	s_waitcnt lgkmcnt(3)
	v_mfma_f32_16x16x32_bf16 v[62:65], v[172:175], v[70:73], 0
	s_waitcnt lgkmcnt(2)
	v_mfma_f32_16x16x32_bf16 v[62:65], v[188:191], v[74:77], v[62:65]
	s_waitcnt lgkmcnt(1)
	v_mfma_f32_16x16x32_bf16 v[62:65], v[212:215], v[78:81], v[62:65]
	s_waitcnt lgkmcnt(0)
	v_mfma_f32_16x16x32_bf16 v[62:65], v[228:231], v[82:85], v[62:65]
	s_or_b64 s[0:1], s[76:77], s[8:9]
	s_and_b64 vcc, s[0:1], s[40:41]
	v_cndmask_b32_e32 v2, v203, v86, vcc
	s_and_b64 vcc, s[0:1], s[42:43]
	v_cndmask_b32_e32 v4, v203, v87, vcc
	s_and_b64 vcc, s[0:1], s[44:45]
	v_cndmask_b32_e32 v66, v203, v88, vcc
	s_and_b64 vcc, s[0:1], s[46:47]
	v_cndmask_b32_e32 v67, v203, v89, vcc
	s_or_b64 vcc, s[76:77], s[12:13]
	s_and_b64 s[0:1], vcc, s[40:41]
	v_cndmask_b32_e64 v69, v203, v90, s[0:1]
	s_and_b64 s[0:1], vcc, s[42:43]
	v_max3_f32 v5, v2, s92, v4
	v_cndmask_b32_e32 v68, v203, v168, vcc
	v_cndmask_b32_e32 v70, v203, v169, vcc
	v_cndmask_b32_e64 v71, v203, v91, s[0:1]
	v_cndmask_b32_e32 v73, v203, v170, vcc
	s_and_b64 s[0:1], vcc, s[44:45]
	v_cndmask_b32_e32 v75, v203, v171, vcc
	s_and_b64 vcc, vcc, s[46:47]
	v_max3_f32 v5, v5, v66, v67
	v_cndmask_b32_e32 v76, v203, v93, vcc
	s_or_b64 vcc, s[76:77], s[14:15]
	v_max3_f32 v5, v5, v68, v70
	v_cndmask_b32_e32 v77, v203, v176, vcc
	v_cndmask_b32_e32 v78, v203, v134, vcc
	v_cndmask_b32_e32 v79, v203, v177, vcc
	v_cndmask_b32_e32 v80, v203, v135, vcc
	v_cndmask_b32_e32 v81, v203, v178, vcc
	v_cndmask_b32_e32 v82, v203, v136, vcc
	v_cndmask_b32_e32 v83, v203, v179, vcc
	v_cndmask_b32_e32 v84, v203, v137, vcc
	s_or_b64 vcc, s[76:77], s[26:27]
	v_cndmask_b32_e64 v74, v203, v92, s[0:1]
	v_max3_f32 v5, v5, v73, v75
	v_cndmask_b32_e32 v85, v203, v184, vcc
	v_cndmask_b32_e32 v86, v203, v138, vcc
	v_cndmask_b32_e32 v87, v203, v185, vcc
	v_cndmask_b32_e32 v88, v203, v139, vcc
	v_cndmask_b32_e32 v89, v203, v186, vcc
	v_cndmask_b32_e32 v90, v203, v140, vcc
	v_cndmask_b32_e32 v91, v203, v187, vcc
	v_cndmask_b32_e32 v92, v203, v141, vcc
	s_or_b64 vcc, s[76:77], s[34:35]
	v_max3_f32 v5, v5, v77, v79
	v_cndmask_b32_e32 v93, v203, v192, vcc
	v_cndmask_b32_e32 v133, v203, v142, vcc
	v_cndmask_b32_e32 v134, v203, v193, vcc
	v_cndmask_b32_e32 v135, v203, v143, vcc
	v_cndmask_b32_e32 v136, v203, v194, vcc
	v_cndmask_b32_e32 v137, v203, v144, vcc
	v_cndmask_b32_e32 v138, v203, v195, vcc
	v_cndmask_b32_e32 v139, v203, v145, vcc
	s_or_b64 vcc, s[76:77], s[36:37]
	v_max3_f32 v5, v5, v81, v83
	v_cndmask_b32_e32 v140, v203, v208, vcc
	v_cndmask_b32_e32 v141, v203, v146, vcc
	v_cndmask_b32_e32 v142, v203, v209, vcc
	v_cndmask_b32_e32 v143, v203, v147, vcc
	v_cndmask_b32_e32 v144, v203, v210, vcc
	v_cndmask_b32_e32 v145, v203, v148, vcc
	v_cndmask_b32_e32 v146, v203, v211, vcc
	v_cndmask_b32_e32 v147, v203, v149, vcc
	s_or_b64 vcc, s[76:77], s[56:57]
	v_max3_f32 v5, v5, v85, v87
	v_cndmask_b32_e32 v148, v203, v216, vcc
	v_cndmask_b32_e32 v149, v203, v150, vcc
	v_cndmask_b32_e32 v150, v203, v217, vcc
	v_cndmask_b32_e32 v151, v203, v151, vcc
	v_cndmask_b32_e32 v158, v203, v218, vcc
	v_cndmask_b32_e32 v152, v203, v152, vcc
	v_cndmask_b32_e32 v159, v203, v219, vcc
	v_cndmask_b32_e32 v153, v203, v153, vcc
	s_or_b64 vcc, s[76:77], s[62:63]
	v_max3_f32 v72, v69, s92, v71
	v_max3_f32 v5, v5, v89, v91
	v_cndmask_b32_e32 v160, v203, v224, vcc
	v_cndmask_b32_e32 v154, v203, v154, vcc
	v_cndmask_b32_e32 v161, v203, v225, vcc
	v_cndmask_b32_e32 v155, v203, v155, vcc
	v_cndmask_b32_e32 v162, v203, v226, vcc
	v_cndmask_b32_e32 v156, v203, v156, vcc
	v_cndmask_b32_e32 v163, v203, v227, vcc
	v_cndmask_b32_e32 v157, v203, v157, vcc
	s_or_b64 vcc, s[76:77], s[66:67]
	v_max3_f32 v72, v72, v74, v76
	v_max3_f32 v5, v5, v93, v134
	s_and_b64 s[0:1], vcc, s[48:49]
	v_max3_f32 v72, v72, v78, v80
	v_max3_f32 v5, v5, v136, v138
	v_cndmask_b32_e64 v54, v203, v54, s[0:1]
	s_and_b64 s[0:1], vcc, s[50:51]
	v_max3_f32 v72, v72, v82, v84
	v_max3_f32 v5, v5, v140, v142
	v_cndmask_b32_e64 v55, v203, v55, s[0:1]
	s_and_b64 s[0:1], vcc, s[52:53]
	v_max3_f32 v72, v72, v86, v88
	v_max3_f32 v5, v5, v144, v146
	v_cndmask_b32_e64 v56, v203, v56, s[0:1]
	s_and_b64 s[0:1], vcc, s[54:55]
	v_max3_f32 v72, v72, v90, v92
	v_max3_f32 v5, v5, v148, v150
	v_cndmask_b32_e64 v57, v203, v57, s[0:1]
	s_or_b64 s[0:1], s[76:77], s[10:11]
	v_max3_f32 v72, v72, v133, v135
	v_max3_f32 v5, v5, v158, v159
	v_cndmask_b32_e32 v58, v203, v58, vcc
	v_cndmask_b32_e32 v59, v203, v59, vcc
	v_cndmask_b32_e32 v60, v203, v60, vcc
	v_cndmask_b32_e32 v61, v203, v61, vcc
	s_and_b64 vcc, s[0:1], s[48:49]
	v_and_b32_e32 v103, 64, v198
	v_max3_f32 v72, v72, v137, v139
	v_max3_f32 v5, v5, v160, v161
	v_cndmask_b32_e32 v62, v203, v62, vcc
	s_and_b64 vcc, s[0:1], s[50:51]
	v_xor_b32_e32 v99, 16, v198
	v_add_u32_e32 v103, 64, v103
	v_max3_f32 v72, v72, v141, v143
	v_max3_f32 v5, v5, v162, v163
	v_cndmask_b32_e32 v63, v203, v63, vcc
	v_cmp_lt_i32_e32 vcc, v99, v103
	v_max3_f32 v72, v72, v145, v147
	v_max3_f32 v5, v5, v54, v55
	v_cndmask_b32_e32 v99, v198, v99, vcc
	v_max3_f32 v72, v72, v149, v151
	v_max3_f32 v5, v5, v56, v57
	v_lshlrev_b32_e32 v168, 2, v99
	v_max3_f32 v72, v72, v152, v153
	ds_bpermute_b32 v99, v168, v5
	v_max3_f32 v72, v72, v154, v155
	v_max3_f32 v72, v72, v156, v157
	v_max3_f32 v72, v72, v58, v59
	s_and_b64 vcc, s[0:1], s[52:53]
	v_max3_f32 v72, v72, v60, v61
	v_cndmask_b32_e32 v64, v203, v64, vcc
	s_and_b64 vcc, s[0:1], s[54:55]
	v_max3_f32 v72, v72, v62, v63
	v_cndmask_b32_e32 v65, v203, v65, vcc
	s_waitcnt lgkmcnt(0)
	v_max_f32_e32 v99, v99, v99
	v_max3_f32 v72, v72, v64, v65
	v_max_f32_e32 v5, v5, v99
	v_xor_b32_e32 v99, 32, v198
	v_cmp_lt_i32_e32 vcc, v99, v103
	ds_bpermute_b32 v103, v168, v72
	s_waitcnt lgkmcnt(0)
	v_max_f32_e32 v103, v103, v103
	v_cndmask_b32_e32 v99, v198, v99, vcc
	v_lshlrev_b32_e32 v169, 2, v99
	ds_bpermute_b32 v99, v169, v5
	v_max_f32_e32 v72, v72, v103
	ds_bpermute_b32 v170, v169, v72
	s_andn2_b64 vcc, exec, s[60:61]
	s_waitcnt lgkmcnt(1)
	v_max_f32_e32 v99, v99, v99
	v_max_f32_e32 v103, v5, v99
	s_waitcnt lgkmcnt(0)
	v_max_f32_e32 v5, v170, v170
	v_max_f32_e32 v99, v72, v5
	v_sub_f32_e32 v78, v78, v99
	v_exp_f32_e32 v170, v78
	v_sub_f32_e32 v78, v79, v103
	v_sub_f32_e32 v79, v80, v99
	v_sub_f32_e32 v80, v82, v99
	v_sub_f32_e32 v82, v86, v99
	v_sub_f32_e32 v86, v89, v103
	v_exp_f32_e32 v173, v86
	v_sub_f32_e32 v86, v90, v99
	v_exp_f32_e32 v174, v86
	v_sub_f32_e32 v86, v91, v103
	v_exp_f32_e32 v175, v86
	v_sub_f32_e32 v86, v92, v99
	v_exp_f32_e32 v176, v86
	v_sub_f32_e32 v86, v93, v103
	v_exp_f32_e32 v177, v86
	v_sub_f32_e32 v86, v133, v99
	v_exp_f32_e32 v178, v86
	v_sub_f32_e32 v86, v134, v103
	v_exp_f32_e32 v179, v86
	v_sub_f32_e32 v86, v135, v99
	v_sub_f32_e32 v2, v2, v103
	v_sub_f32_e32 v69, v69, v99
	v_exp_f32_e32 v180, v86
	v_sub_f32_e32 v86, v136, v103
	v_exp_f32_e32 v2, v2
	v_sub_f32_e32 v4, v4, v103
	v_exp_f32_e32 v69, v69
	v_sub_f32_e32 v71, v71, v99
	v_exp_f32_e32 v181, v86
	v_sub_f32_e32 v86, v137, v99
	v_exp_f32_e32 v4, v4
	v_sub_f32_e32 v66, v66, v103
	v_exp_f32_e32 v71, v71
	v_sub_f32_e32 v74, v74, v99
	v_exp_f32_e32 v137, v86
	v_sub_f32_e32 v86, v138, v103
	v_exp_f32_e32 v66, v66
	v_sub_f32_e32 v67, v67, v103
	v_exp_f32_e32 v74, v74
	v_sub_f32_e32 v76, v76, v99
	v_exp_f32_e32 v138, v86
	v_sub_f32_e32 v86, v139, v99
	v_exp_f32_e32 v67, v67
	v_sub_f32_e32 v68, v68, v103
	v_exp_f32_e32 v76, v76
	v_exp_f32_e32 v139, v86
	v_sub_f32_e32 v86, v140, v103
	v_add_f32_e32 v5, 0, v2
	v_exp_f32_e32 v68, v68
	v_sub_f32_e32 v70, v70, v103
	v_sub_f32_e32 v72, v73, v103
	v_add_f32_e32 v73, 0, v69
	v_exp_f32_e32 v140, v86
	v_sub_f32_e32 v86, v141, v99
	v_add_f32_e32 v5, v4, v5
	v_exp_f32_e32 v70, v70
	v_add_f32_e32 v73, v71, v73
	v_exp_f32_e32 v171, v79
	v_exp_f32_e32 v141, v86
	v_sub_f32_e32 v86, v142, v103
	v_add_f32_e32 v5, v66, v5
	v_exp_f32_e32 v72, v72
	v_sub_f32_e32 v75, v75, v103
	v_add_f32_e32 v73, v74, v73
	v_sub_f32_e32 v79, v81, v103
	v_exp_f32_e32 v172, v80
	v_sub_f32_e32 v81, v84, v99
	v_exp_f32_e32 v142, v86
	v_sub_f32_e32 v86, v143, v99
	v_add_f32_e32 v5, v67, v5
	v_exp_f32_e32 v75, v75
	v_sub_f32_e32 v77, v77, v103
	v_add_f32_e32 v73, v76, v73
	v_sub_f32_e32 v80, v83, v103
	v_exp_f32_e32 v83, v81
	v_exp_f32_e32 v143, v86
	v_sub_f32_e32 v86, v144, v103
	v_add_f32_e32 v5, v68, v5
	v_exp_f32_e32 v77, v77
	v_add_f32_e32 v73, v170, v73
	v_sub_f32_e32 v81, v85, v103
	v_exp_f32_e32 v84, v82
	v_sub_f32_e32 v85, v88, v99
	v_exp_f32_e32 v144, v86
	v_sub_f32_e32 v86, v145, v99
	v_add_f32_e32 v5, v70, v5
	v_exp_f32_e32 v78, v78
	v_add_f32_e32 v73, v171, v73
	v_exp_f32_e32 v85, v85
	v_exp_f32_e32 v145, v86
	v_sub_f32_e32 v86, v146, v103
	v_add_f32_e32 v5, v72, v5
	v_exp_f32_e32 v79, v79
	v_add_f32_e32 v73, v172, v73
	v_exp_f32_e32 v146, v86
	v_sub_f32_e32 v86, v147, v99
	v_add_f32_e32 v5, v75, v5
	v_exp_f32_e32 v80, v80
	v_add_f32_e32 v73, v83, v73
	v_exp_f32_e32 v147, v86
	v_sub_f32_e32 v86, v148, v103
	v_add_f32_e32 v5, v77, v5
	v_exp_f32_e32 v81, v81
	v_sub_f32_e32 v82, v87, v103
	v_add_f32_e32 v73, v84, v73
	v_exp_f32_e32 v148, v86
	v_sub_f32_e32 v86, v149, v99
	v_add_f32_e32 v5, v78, v5
	v_exp_f32_e32 v82, v82
	v_add_f32_e32 v73, v85, v73
	v_exp_f32_e32 v149, v86
	v_sub_f32_e32 v86, v150, v103
	v_add_f32_e32 v5, v79, v5
	v_add_f32_e32 v73, v174, v73
	v_exp_f32_e32 v150, v86
	v_sub_f32_e32 v86, v151, v99
	v_add_f32_e32 v5, v80, v5
	v_add_f32_e32 v73, v176, v73
	v_exp_f32_e32 v151, v86
	v_sub_f32_e32 v86, v158, v103
	v_add_f32_e32 v5, v81, v5
	v_add_f32_e32 v73, v178, v73
	v_exp_f32_e32 v158, v86
	v_sub_f32_e32 v86, v152, v99
	v_add_f32_e32 v5, v82, v5
	v_add_f32_e32 v73, v180, v73
	v_exp_f32_e32 v152, v86
	v_sub_f32_e32 v86, v159, v103
	v_add_f32_e32 v5, v173, v5
	v_add_f32_e32 v73, v137, v73
	v_exp_f32_e32 v159, v86
	v_sub_f32_e32 v86, v153, v99
	v_add_f32_e32 v5, v175, v5
	v_add_f32_e32 v73, v139, v73
	v_exp_f32_e32 v153, v86
	v_sub_f32_e32 v86, v160, v103
	v_add_f32_e32 v5, v177, v5
	v_add_f32_e32 v73, v141, v73
	v_exp_f32_e32 v160, v86
	v_sub_f32_e32 v86, v154, v99
	v_add_f32_e32 v5, v179, v5
	v_add_f32_e32 v73, v143, v73
	v_exp_f32_e32 v154, v86
	v_sub_f32_e32 v86, v161, v103
	v_add_f32_e32 v5, v181, v5
	v_add_f32_e32 v73, v145, v73
	v_exp_f32_e32 v161, v86
	v_sub_f32_e32 v86, v155, v99
	v_add_f32_e32 v5, v138, v5
	v_add_f32_e32 v73, v147, v73
	v_exp_f32_e32 v155, v86
	v_sub_f32_e32 v86, v162, v103
	v_add_f32_e32 v5, v140, v5
	v_add_f32_e32 v73, v149, v73
	v_exp_f32_e32 v162, v86
	v_sub_f32_e32 v86, v156, v99
	v_add_f32_e32 v5, v142, v5
	v_add_f32_e32 v73, v151, v73
	v_exp_f32_e32 v156, v86
	v_sub_f32_e32 v86, v163, v103
	v_add_f32_e32 v5, v144, v5
	v_add_f32_e32 v73, v152, v73
	v_exp_f32_e32 v163, v86
	v_sub_f32_e32 v86, v157, v99
	v_add_f32_e32 v5, v146, v5
	v_add_f32_e32 v73, v153, v73
	v_exp_f32_e32 v157, v86
	v_sub_f32_e32 v58, v58, v99
	v_add_f32_e32 v5, v148, v5
	v_add_f32_e32 v73, v154, v73
	v_exp_f32_e32 v58, v58
	v_sub_f32_e32 v59, v59, v99
	v_add_f32_e32 v5, v150, v5
	v_add_f32_e32 v73, v155, v73
	v_exp_f32_e32 v59, v59
	v_sub_f32_e32 v60, v60, v99
	v_add_f32_e32 v5, v158, v5
	v_add_f32_e32 v73, v156, v73
	v_exp_f32_e32 v60, v60
	v_sub_f32_e32 v61, v61, v99
	v_add_f32_e32 v5, v159, v5
	v_sub_f32_e32 v54, v54, v103
	v_add_f32_e32 v73, v157, v73
	v_exp_f32_e32 v61, v61
	v_sub_f32_e32 v62, v62, v99
	v_add_f32_e32 v5, v160, v5
	v_exp_f32_e32 v54, v54
	v_sub_f32_e32 v55, v55, v103
	v_add_f32_e32 v73, v58, v73
	v_exp_f32_e32 v182, v62
	v_sub_f32_e32 v63, v63, v99
	v_add_f32_e32 v5, v161, v5
	v_exp_f32_e32 v55, v55
	v_sub_f32_e32 v56, v56, v103
	v_add_f32_e32 v73, v59, v73
	v_exp_f32_e32 v183, v63
	v_sub_f32_e32 v63, v64, v99
	v_add_f32_e32 v5, v162, v5
	v_exp_f32_e32 v56, v56
	v_sub_f32_e32 v57, v57, v103
	v_add_f32_e32 v62, v60, v73
	v_exp_f32_e32 v184, v63
	v_sub_f32_e32 v63, v65, v99
	v_add_f32_e32 v5, v163, v5
	v_exp_f32_e32 v57, v57
	v_add_f32_e32 v62, v61, v62
	v_exp_f32_e32 v185, v63
	v_add_f32_e32 v5, v54, v5
	v_add_f32_e32 v62, v182, v62
	v_add_f32_e32 v5, v55, v5
	v_add_f32_e32 v62, v183, v62
	v_add_f32_e32 v5, v56, v5
	v_add_f32_e32 v62, v184, v62
	v_add_f32_e32 v5, v57, v5
	v_add_f32_e32 v62, v185, v62
	ds_bpermute_b32 v63, v168, v5
	ds_bpermute_b32 v64, v168, v62
	v_cvt_pk_bf16_f32 v86, v2, v4
	v_cvt_pk_bf16_f32 v87, v66, v67
	v_cvt_pk_bf16_f32 v88, v68, v70
	s_waitcnt lgkmcnt(1)
	v_add_f32_e32 v135, v5, v63
	s_waitcnt lgkmcnt(0)
	v_add_f32_e32 v133, v62, v64
	ds_bpermute_b32 v136, v169, v135
	ds_bpermute_b32 v134, v169, v133
	v_cvt_pk_bf16_f32 v89, v72, v75
	v_cvt_pk_bf16_f32 v90, v3, v3
	v_cvt_pk_bf16_f32 v91, v3, v3
	v_cvt_pk_bf16_f32 v92, v69, v71
	v_cvt_pk_bf16_f32 v93, v74, v76
	v_cvt_pk_bf16_f32 v78, v77, v78
	v_cvt_pk_bf16_f32 v79, v79, v80
	v_cvt_pk_bf16_f32 v80, v81, v82
	v_cvt_pk_bf16_f32 v81, v173, v175
	v_cvt_pk_bf16_f32 v82, v170, v171
	v_cvt_pk_bf16_f32 v83, v172, v83
	v_cvt_pk_bf16_f32 v84, v84, v85
	v_cvt_pk_bf16_f32 v85, v174, v176
	v_cvt_pk_bf16_f32 v70, v177, v179
	v_cvt_pk_bf16_f32 v71, v181, v138
	v_cvt_pk_bf16_f32 v72, v140, v142
	v_cvt_pk_bf16_f32 v73, v144, v146
	v_cvt_pk_bf16_f32 v74, v178, v180
	v_cvt_pk_bf16_f32 v75, v137, v139
	v_cvt_pk_bf16_f32 v76, v141, v143
	v_cvt_pk_bf16_f32 v77, v145, v147
	v_cvt_pk_bf16_f32 v62, v148, v150
	v_cvt_pk_bf16_f32 v63, v158, v159
	v_cvt_pk_bf16_f32 v64, v160, v161
	v_cvt_pk_bf16_f32 v65, v162, v163
	v_cvt_pk_bf16_f32 v66, v149, v151
	v_cvt_pk_bf16_f32 v67, v152, v153
	v_cvt_pk_bf16_f32 v68, v154, v155
	v_cvt_pk_bf16_f32 v69, v156, v157
	v_cvt_pk_bf16_f32 v54, v54, v55
	v_cvt_pk_bf16_f32 v55, v56, v57
	v_cvt_pk_bf16_f32 v56, v3, v3
	v_cvt_pk_bf16_f32 v57, v3, v3
	v_cvt_pk_bf16_f32 v58, v58, v59
	v_cvt_pk_bf16_f32 v59, v60, v61
	v_cvt_pk_bf16_f32 v60, v182, v183
	v_cvt_pk_bf16_f32 v61, v184, v185
	s_waitcnt lgkmcnt(0)
	s_barrier
	ds_write_b128 v118, v[6:9]
	ds_write_b128 v118, v[10:13] offset:8192
	ds_write_b128 v118, v[14:17] offset:16384
	ds_write_b128 v118, v[18:21] offset:24576
	s_waitcnt vmcnt(7)
	ds_write_b128 v118, v[22:25] offset:32768
	s_waitcnt vmcnt(6)
	ds_write_b128 v118, v[26:29] offset:40960
	s_waitcnt vmcnt(5)
	ds_write_b128 v118, v[30:33] offset:49152
	s_waitcnt vmcnt(4)
	ds_write_b128 v118, v[34:37] offset:57344
	s_waitcnt vmcnt(3)
	ds_write_b128 v123, v[38:41]
	s_waitcnt vmcnt(2)
	ds_write_b128 v124, v[42:45]
	s_waitcnt vmcnt(1)
	ds_write_b128 v125, v[46:49]
	s_waitcnt vmcnt(0)
	ds_write_b128 v126, v[50:53]
	s_waitcnt lgkmcnt(0)
	s_barrier
	s_cbranch_vccnz .LBB0_725
	s_lshl_b32 s1, s81, 24
	s_lshl_b32 s60, s82, 20
	v_lshl_or_b32 v2, v132, 8, v106
	s_add_i32 s1, s1, s60
	s_lshl_b32 s0, s80, 1
	v_add_u32_e32 v46, s1, v2
	s_lshl_b32 s1, s79, 16
	s_cmp_lt_i32 s79, 1
	v_add_u32_e32 v47, s1, v108
	s_cbranch_scc1 .LBB0_723
	v_lshl_add_u32 v2, v47, s0, v46
	v_add_u32_e32 v4, 0x2000, v47
	v_lshl_add_u32 v4, v4, s0, v46
	global_load_dwordx4 v[6:9], v2, s[70:71]
	global_load_dwordx4 v[10:13], v4, s[70:71]
	v_add_u32_e32 v2, 0x4000, v47
	v_lshl_add_u32 v2, v2, s0, v46
	v_add_u32_e32 v4, 0x6000, v47
	v_lshl_add_u32 v4, v4, s0, v46
	global_load_dwordx4 v[14:17], v2, s[70:71]
	global_load_dwordx4 v[18:21], v4, s[70:71]
	s_branch .LBB0_724

.LBB0_725:
	s_waitcnt lgkmcnt(13)
	v_add_f32_e32 v2, v135, v136
	ds_read_b64_tr_b16 v[136:137], v109 offset:0
	ds_read_b64_tr_b16 v[138:139], v109 offset:0x1000
	ds_read_b64_tr_b16 v[140:141], v110 offset:0
	ds_read_b64_tr_b16 v[142:143], v110 offset:0x1000
	ds_read_b64_tr_b16 v[144:145], v111 offset:0
	ds_read_b64_tr_b16 v[146:147], v111 offset:0x1000
	ds_read_b64_tr_b16 v[148:149], v112 offset:0
	ds_read_b64_tr_b16 v[150:151], v112 offset:0x1000
	ds_read_b64_tr_b16 v[152:153], v113 offset:0
	ds_read_b64_tr_b16 v[154:155], v113 offset:0x1000
	ds_read_b64_tr_b16 v[156:157], v114 offset:0
	ds_read_b64_tr_b16 v[158:159], v114 offset:0x1000
	ds_read_b64_tr_b16 v[160:161], v115 offset:0
	ds_read_b64_tr_b16 v[162:163], v115 offset:0x1000
	ds_read_b64_tr_b16 v[168:169], v116 offset:0
	ds_read_b64_tr_b16 v[170:171], v116 offset:0x1000
	s_waitcnt lgkmcnt(8)
	s_nop 0
	v_mfma_f32_16x16x32_bf16 v[172:175], v[136:139], v[86:89], 0
	v_mfma_f32_16x16x32_bf16 v[136:139], v[136:139], v[90:93], 0
	v_mfma_f32_16x16x32_bf16 v[176:179], v[140:143], v[86:89], 0
	v_mfma_f32_16x16x32_bf16 v[140:143], v[140:143], v[90:93], 0
	v_mfma_f32_16x16x32_bf16 v[180:183], v[144:147], v[86:89], 0
	v_mfma_f32_16x16x32_bf16 v[144:147], v[144:147], v[90:93], 0
	v_mfma_f32_16x16x32_bf16 v[184:187], v[148:151], v[86:89], 0
	v_mfma_f32_16x16x32_bf16 v[148:151], v[148:151], v[90:93], 0
	ds_read_b64_tr_b16 v[188:189], v109 offset:0x2000
	ds_read_b64_tr_b16 v[190:191], v109 offset:0x3000
	ds_read_b64_tr_b16 v[192:193], v110 offset:0x2000
	ds_read_b64_tr_b16 v[194:195], v110 offset:0x3000
	ds_read_b64_tr_b16 v[204:205], v111 offset:0x2000
	ds_read_b64_tr_b16 v[206:207], v111 offset:0x3000
	ds_read_b64_tr_b16 v[208:209], v112 offset:0x2000
	ds_read_b64_tr_b16 v[210:211], v112 offset:0x3000
	s_waitcnt lgkmcnt(8)
	v_mfma_f32_16x16x32_bf16 v[212:215], v[152:155], v[86:89], 0
	v_mfma_f32_16x16x32_bf16 v[216:219], v[156:159], v[86:89], 0
	v_mfma_f32_16x16x32_bf16 v[220:223], v[160:163], v[86:89], 0
	v_mfma_f32_16x16x32_bf16 v[86:89], v[168:171], v[86:89], 0
	v_mfma_f32_16x16x32_bf16 v[152:155], v[152:155], v[90:93], 0
	v_mfma_f32_16x16x32_bf16 v[156:159], v[156:159], v[90:93], 0
	v_mfma_f32_16x16x32_bf16 v[160:163], v[160:163], v[90:93], 0
	v_mfma_f32_16x16x32_bf16 v[90:93], v[168:171], v[90:93], 0
	ds_read_b64_tr_b16 v[168:169], v113 offset:0x2000
	ds_read_b64_tr_b16 v[170:171], v113 offset:0x3000
	ds_read_b64_tr_b16 v[224:225], v114 offset:0x2000
	ds_read_b64_tr_b16 v[226:227], v114 offset:0x3000
	ds_read_b64_tr_b16 v[228:229], v115 offset:0x2000
	ds_read_b64_tr_b16 v[230:231], v115 offset:0x3000
	ds_read_b64_tr_b16 v[232:233], v116 offset:0x2000
	ds_read_b64_tr_b16 v[234:235], v116 offset:0x3000
	s_waitcnt lgkmcnt(8)
	v_mfma_f32_16x16x32_bf16 v[172:175], v[188:191], v[78:81], v[172:175]
	v_mfma_f32_16x16x32_bf16 v[136:139], v[188:191], v[82:85], v[136:139]
	v_mfma_f32_16x16x32_bf16 v[176:179], v[192:195], v[78:81], v[176:179]
	v_mfma_f32_16x16x32_bf16 v[140:143], v[192:195], v[82:85], v[140:143]
	v_mfma_f32_16x16x32_bf16 v[180:183], v[204:207], v[78:81], v[180:183]
	v_mfma_f32_16x16x32_bf16 v[144:147], v[204:207], v[82:85], v[144:147]
	v_mfma_f32_16x16x32_bf16 v[184:187], v[208:211], v[78:81], v[184:187]
	v_mfma_f32_16x16x32_bf16 v[148:151], v[208:211], v[82:85], v[148:151]
	ds_read_b64_tr_b16 v[188:189], v109 offset:0x4000
	ds_read_b64_tr_b16 v[190:191], v109 offset:0x5000
	ds_read_b64_tr_b16 v[192:193], v110 offset:0x4000
	ds_read_b64_tr_b16 v[194:195], v110 offset:0x5000
	ds_read_b64_tr_b16 v[204:205], v111 offset:0x4000
	ds_read_b64_tr_b16 v[206:207], v111 offset:0x5000
	ds_read_b64_tr_b16 v[208:209], v112 offset:0x4000
	ds_read_b64_tr_b16 v[210:211], v112 offset:0x5000
	s_waitcnt lgkmcnt(8)
	v_mfma_f32_16x16x32_bf16 v[212:215], v[168:171], v[78:81], v[212:215]
	v_mfma_f32_16x16x32_bf16 v[152:155], v[168:171], v[82:85], v[152:155]
	v_mfma_f32_16x16x32_bf16 v[168:171], v[224:227], v[78:81], v[216:219]
	v_mfma_f32_16x16x32_bf16 v[156:159], v[224:227], v[82:85], v[156:159]
	v_mfma_f32_16x16x32_bf16 v[216:219], v[228:231], v[78:81], v[220:223]
	v_mfma_f32_16x16x32_bf16 v[160:163], v[228:231], v[82:85], v[160:163]
	v_mfma_f32_16x16x32_bf16 v[78:81], v[232:235], v[78:81], v[86:89]
	v_mfma_f32_16x16x32_bf16 v[82:85], v[232:235], v[82:85], v[90:93]
	ds_read_b64_tr_b16 v[86:87], v113 offset:0x4000
	ds_read_b64_tr_b16 v[88:89], v113 offset:0x5000
	ds_read_b64_tr_b16 v[90:91], v114 offset:0x4000
	ds_read_b64_tr_b16 v[92:93], v114 offset:0x5000
	ds_read_b64_tr_b16 v[220:221], v115 offset:0x4000
	ds_read_b64_tr_b16 v[222:223], v115 offset:0x5000
	ds_read_b64_tr_b16 v[224:225], v116 offset:0x4000
	ds_read_b64_tr_b16 v[226:227], v116 offset:0x5000
	s_waitcnt lgkmcnt(8)
	v_mfma_f32_16x16x32_bf16 v[172:175], v[188:191], v[70:73], v[172:175]
	v_mfma_f32_16x16x32_bf16 v[136:139], v[188:191], v[74:77], v[136:139]
	v_mfma_f32_16x16x32_bf16 v[176:179], v[192:195], v[70:73], v[176:179]
	v_mfma_f32_16x16x32_bf16 v[140:143], v[192:195], v[74:77], v[140:143]
	v_mfma_f32_16x16x32_bf16 v[180:183], v[204:207], v[70:73], v[180:183]
	v_mfma_f32_16x16x32_bf16 v[144:147], v[204:207], v[74:77], v[144:147]
	v_mfma_f32_16x16x32_bf16 v[184:187], v[208:211], v[70:73], v[184:187]
	v_mfma_f32_16x16x32_bf16 v[148:151], v[208:211], v[74:77], v[148:151]
	ds_read_b64_tr_b16 v[188:189], v109 offset:0x6000
	ds_read_b64_tr_b16 v[190:191], v109 offset:0x7000
	ds_read_b64_tr_b16 v[192:193], v110 offset:0x6000
	ds_read_b64_tr_b16 v[194:195], v110 offset:0x7000
	ds_read_b64_tr_b16 v[204:205], v111 offset:0x6000
	ds_read_b64_tr_b16 v[206:207], v111 offset:0x7000
	ds_read_b64_tr_b16 v[208:209], v112 offset:0x6000
	ds_read_b64_tr_b16 v[210:211], v112 offset:0x7000
	s_waitcnt lgkmcnt(8)
	v_mfma_f32_16x16x32_bf16 v[212:215], v[86:89], v[70:73], v[212:215]
	v_mfma_f32_16x16x32_bf16 v[86:89], v[86:89], v[74:77], v[152:155]
	v_mfma_f32_16x16x32_bf16 v[152:155], v[90:93], v[70:73], v[168:171]
	v_mfma_f32_16x16x32_bf16 v[90:93], v[90:93], v[74:77], v[156:159]
	v_mfma_f32_16x16x32_bf16 v[156:159], v[220:223], v[70:73], v[216:219]
	v_mfma_f32_16x16x32_bf16 v[160:163], v[220:223], v[74:77], v[160:163]
	v_mfma_f32_16x16x32_bf16 v[70:73], v[224:227], v[70:73], v[78:81]
	v_mfma_f32_16x16x32_bf16 v[74:77], v[224:227], v[74:77], v[82:85]
	ds_read_b64_tr_b16 v[78:79], v113 offset:0x6000
	ds_read_b64_tr_b16 v[80:81], v113 offset:0x7000
	ds_read_b64_tr_b16 v[82:83], v114 offset:0x6000
	ds_read_b64_tr_b16 v[84:85], v114 offset:0x7000
	ds_read_b64_tr_b16 v[168:169], v115 offset:0x6000
	ds_read_b64_tr_b16 v[170:171], v115 offset:0x7000
	ds_read_b64_tr_b16 v[216:217], v116 offset:0x6000
	ds_read_b64_tr_b16 v[218:219], v116 offset:0x7000
	s_waitcnt lgkmcnt(8)
	v_mfma_f32_16x16x32_bf16 v[172:175], v[188:191], v[62:65], v[172:175]
	v_mfma_f32_16x16x32_bf16 v[136:139], v[188:191], v[66:69], v[136:139]
	v_mfma_f32_16x16x32_bf16 v[176:179], v[192:195], v[62:65], v[176:179]
	v_mfma_f32_16x16x32_bf16 v[140:143], v[192:195], v[66:69], v[140:143]
	v_mfma_f32_16x16x32_bf16 v[180:183], v[204:207], v[62:65], v[180:183]
	v_mfma_f32_16x16x32_bf16 v[144:147], v[204:207], v[66:69], v[144:147]
	v_mfma_f32_16x16x32_bf16 v[184:187], v[208:211], v[62:65], v[184:187]
	v_mfma_f32_16x16x32_bf16 v[148:151], v[208:211], v[66:69], v[148:151]
	ds_read_b64_tr_b16 v[188:189], v109 offset:0x8000
	ds_read_b64_tr_b16 v[190:191], v109 offset:0x9000
	ds_read_b64_tr_b16 v[192:193], v110 offset:0x8000
	ds_read_b64_tr_b16 v[194:195], v110 offset:0x9000
	ds_read_b64_tr_b16 v[204:205], v111 offset:0x8000
	ds_read_b64_tr_b16 v[206:207], v111 offset:0x9000
	ds_read_b64_tr_b16 v[208:209], v112 offset:0x8000
	ds_read_b64_tr_b16 v[210:211], v112 offset:0x9000
	s_waitcnt lgkmcnt(8)
	v_mfma_f32_16x16x32_bf16 v[212:215], v[78:81], v[62:65], v[212:215]
	v_mfma_f32_16x16x32_bf16 v[220:223], v[78:81], v[66:69], v[86:89]
	v_mfma_f32_16x16x32_bf16 v[152:155], v[82:85], v[62:65], v[152:155]
	v_mfma_f32_16x16x32_bf16 v[90:93], v[82:85], v[66:69], v[90:93]
	v_mfma_f32_16x16x32_bf16 v[156:159], v[168:171], v[62:65], v[156:159]
	v_mfma_f32_16x16x32_bf16 v[160:163], v[168:171], v[66:69], v[160:163]
	v_mfma_f32_16x16x32_bf16 v[168:171], v[216:219], v[62:65], v[70:73]
	v_mfma_f32_16x16x32_bf16 v[216:219], v[216:219], v[66:69], v[74:77]
	ds_read_b64_tr_b16 v[62:63], v113 offset:0x8000
	ds_read_b64_tr_b16 v[64:65], v113 offset:0x9000
	ds_read_b64_tr_b16 v[66:67], v114 offset:0x8000
	ds_read_b64_tr_b16 v[68:69], v114 offset:0x9000
	ds_read_b64_tr_b16 v[224:225], v115 offset:0x8000
	ds_read_b64_tr_b16 v[226:227], v115 offset:0x9000
	ds_read_b64_tr_b16 v[228:229], v116 offset:0x8000
	ds_read_b64_tr_b16 v[230:231], v116 offset:0x9000
	s_waitcnt lgkmcnt(8)
	v_mfma_f32_16x16x32_bf16 v[86:89], v[188:191], v[58:61], v[136:139]
	v_mfma_f32_16x16x32_bf16 v[82:85], v[192:195], v[58:61], v[140:143]
	v_mfma_f32_16x16x32_bf16 v[78:81], v[204:207], v[58:61], v[144:147]
	v_mfma_f32_16x16x32_bf16 v[70:73], v[208:211], v[58:61], v[148:151]
	v_mfma_f32_16x16x32_bf16 v[172:175], v[188:191], v[54:57], v[172:175]
	v_mfma_f32_16x16x32_bf16 v[136:139], v[192:195], v[54:57], v[176:179]
	v_mfma_f32_16x16x32_bf16 v[140:143], v[204:207], v[54:57], v[180:183]
	v_mfma_f32_16x16x32_bf16 v[144:147], v[208:211], v[54:57], v[184:187]
	s_waitcnt lgkmcnt(0)
	v_mfma_f32_16x16x32_bf16 v[148:151], v[62:65], v[54:57], v[212:215]
	v_mfma_f32_16x16x32_bf16 v[74:77], v[62:65], v[58:61], v[220:223]
	v_mfma_f32_16x16x32_bf16 v[152:155], v[66:69], v[54:57], v[152:155]
	v_mfma_f32_16x16x32_bf16 v[66:69], v[66:69], v[58:61], v[90:93]
	v_mfma_f32_16x16x32_bf16 v[90:93], v[224:227], v[54:57], v[156:159]
	v_mfma_f32_16x16x32_bf16 v[62:65], v[224:227], v[58:61], v[160:163]
	v_mfma_f32_16x16x32_bf16 v[156:159], v[228:231], v[54:57], v[168:171]
	v_mfma_f32_16x16x32_bf16 v[54:57], v[228:231], v[58:61], v[216:219]
	s_lshl_b32 s99, s80, 1
	v_lshl_add_u32 v238, s79, 8, v127
	s_lshl_b32 s100, s81, 4
	s_lshl_b32 s101, s80, 6
	s_add_i32 s100, s100, s82
	v_lshlrev_b32_e32 v236, s99, v238
	v_or_b32_e32 v238, 16, v238
	s_add_i32 s100, s100, s101
	v_lshlrev_b32_e32 v238, s99, v238
	s_ashr_i32 s101, s100, 31
	v_add_u32_e32 v236, v236, v132
	v_add_u32_e32 v238, v238, v132
	s_lshl_b64 s[100:101], s[100:101], 20
	v_ashrrev_i32_e32 v237, 31, v236
	v_ashrrev_i32_e32 v239, 31, v238
	v_lshl_add_u64 v[244:245], v[94:95], 0, s[100:101]
	v_lshlrev_b64 v[236:237], 8, v[236:237]
	v_lshlrev_b64 v[238:239], 8, v[238:239]
	v_lshl_add_u64 v[236:237], v[244:245], 0, v[236:237]
	v_lshl_add_u64 v[238:239], v[244:245], 0, v[238:239]
	global_load_dwordx4 v[204:207], v[236:237], off
	global_load_dwordx4 v[208:211], v[236:237], off offset:64
	global_load_dwordx4 v[212:215], v[236:237], off offset:128
	global_load_dwordx4 v[216:219], v[236:237], off offset:192
	global_load_dwordx4 v[220:223], v[238:239], off
	global_load_dwordx4 v[224:227], v[238:239], off offset:64
	global_load_dwordx4 v[228:231], v[238:239], off offset:128
	global_load_dwordx4 v[192:195], v[238:239], off offset:192
	s_lshl_b32 s60, s20, 12
	s_add_i32 s20, s31, -1
	s_lshl_b64 s[0:1], s[20:21], 20
	s_add_u32 s20, s16, s0
	v_lshl_add_u64 v[4:5], v[96:97], 0, s[24:25]
	s_addc_u32 s24, s17, s1
	v_div_scale_f32 v58, s[0:1], v2, v2, 1.0
	v_rcp_f32_e32 v59, v58
	s_waitcnt lgkmcnt(0)
	s_barrier
	v_fma_f32 v60, -v58, v59, 1.0
	v_fmac_f32_e32 v59, v60, v59
	v_div_scale_f32 v60, vcc, 1.0, v2, 1.0
	v_mul_f32_e32 v61, v60, v59
	v_fma_f32 v135, -v58, v61, v60
	v_fmac_f32_e32 v61, v135, v59
	v_fma_f32 v58, -v58, v61, v60
	v_div_fmas_f32 v58, v58, v59, v61
	v_div_fixup_f32 v135, v58, v2, 1.0
	v_mul_f32_e32 v60, v135, v172
	v_mul_f32_e32 v61, v135, v173
	v_cvt_pk_bf16_f32 v60, v60, v61
	v_mul_f32_e32 v61, v135, v174
	v_lshl_add_u64 v[58:59], v[4:5], 0, v[104:105]
	v_mul_f32_e32 v104, v135, v175
	v_cvt_pk_bf16_f32 v61, v61, v104
	global_store_dwordx2 v[58:59], v[60:61], off
	v_mul_f32_e32 v60, v135, v136
	v_mul_f32_e32 v61, v135, v137
	v_cvt_pk_bf16_f32 v60, v60, v61
	v_mul_f32_e32 v61, v135, v138
	v_mul_f32_e32 v104, v135, v139
	v_cvt_pk_bf16_f32 v61, v61, v104
	global_store_dwordx2 v[58:59], v[60:61], off offset:32
	v_mul_f32_e32 v60, v135, v140
	v_mul_f32_e32 v61, v135, v141
	v_cvt_pk_bf16_f32 v60, v60, v61
	v_mul_f32_e32 v61, v135, v142
	v_mul_f32_e32 v104, v135, v143
	v_cvt_pk_bf16_f32 v61, v61, v104
	global_store_dwordx2 v[58:59], v[60:61], off offset:64
	v_mul_f32_e32 v60, v135, v144
	v_mul_f32_e32 v61, v135, v145
	v_cvt_pk_bf16_f32 v60, v60, v61
	v_mul_f32_e32 v61, v135, v146
	v_mul_f32_e32 v104, v135, v147
	v_cvt_pk_bf16_f32 v61, v61, v104
	global_store_dwordx2 v[58:59], v[60:61], off offset:96
	v_mul_f32_e32 v60, v135, v148
	v_mul_f32_e32 v61, v135, v149
	v_cvt_pk_bf16_f32 v60, v60, v61
	v_mul_f32_e32 v61, v135, v150
	v_mul_f32_e32 v104, v135, v151
	v_cvt_pk_bf16_f32 v61, v61, v104
	global_store_dwordx2 v[58:59], v[60:61], off offset:128
	v_mul_f32_e32 v60, v135, v152
	v_mul_f32_e32 v61, v135, v153
	v_cvt_pk_bf16_f32 v60, v60, v61
	v_mul_f32_e32 v61, v135, v154
	v_mul_f32_e32 v104, v135, v155
	v_cvt_pk_bf16_f32 v61, v61, v104
	global_store_dwordx2 v[58:59], v[60:61], off offset:160
	v_mul_f32_e32 v60, v135, v90
	v_mul_f32_e32 v61, v135, v91
	s_mov_b32 s31, s21
	v_cvt_pk_bf16_f32 v60, v60, v61
	v_mul_f32_e32 v61, v135, v92
	s_lshl_b64 s[0:1], s[30:31], 2
	v_mul_f32_e32 v90, v135, v93
	v_cvt_pk_bf16_f32 v61, v61, v90
	s_add_u32 s0, s20, s0
	global_store_dwordx2 v[58:59], v[60:61], off offset:192
	v_mul_f32_e32 v60, v135, v156
	v_mul_f32_e32 v61, v135, v157
	s_addc_u32 s1, s24, s1
	v_cvt_pk_bf16_f32 v60, v60, v61
	v_mul_f32_e32 v61, v135, v158
	v_mul_f32_e32 v90, v135, v159
	v_cvt_pk_bf16_f32 v61, v61, v90
	global_store_dwordx2 v[58:59], v[60:61], off offset:224
	s_and_saveexec_b64 s[24:25], s[38:39]
	s_cbranch_execz .LBB0_727
	v_log_f32_e32 v2, v2
	v_add_u32_e32 v58, s60, v102
	v_ashrrev_i32_e32 v59, 31, v58
	v_lshlrev_b64 v[58:59], 6, v[58:59]
	v_lshl_add_u64 v[58:59], s[0:1], 0, v[58:59]
	v_add_f32_e32 v2, v103, v2
	global_store_dword v[58:59], v2, off
